# retention: cross term software-pipelined plus cross-tile K-read prefetch in the score loop, on top of v5
# speedup vs baseline: 1.0043x; 1.0043x over previous
; __device__ __forceinline__ unsigned cvt_pk_bf16(float lo, float hi) { const bf16x2_cv v = __builtin_convertvector((f32x2_cv){lo, hi}, bf16x2_cv); return __builtin_bit_cast(unsigned, v); }
; #define LAS __attribute__((address_space(3)))
; __device__ __forceinline__ void retention_fused(const Params& p, LAS unsigned char* lds, int unit) {
;     ...
; #pragma unroll
;         for (int mt = 0; mt < 2; ++mt)
; #pragma unroll
;             for (int nt = 0; nt < 4; ++nt) { u32x2 w; w.x = cvt_pk_bf16(S[mt][nt][0], S[mt][nt][1]); w.y = cvt_pk_bf16(S[mt][nt][2], S[mt][nt][3]);
;                 *(LAS u32x2*)(St + (nt * 16 + fr) * ST_STRIDE + (32 * wid + 16 * mt + fq * 4) * 2) = w; }
; #pragma unroll
;         for (int i = 0; i < 8; ++i) { const int id = tid + i * NTHREADS, row = id >> 5, cc = id & 31; *(LAS u32x4*)(Ks + row * KS_STRIDE + cc * 16) = *(const u32x4*)(Kg + (size_t)(c * 128 + row) * D + cc * 8); }
; #pragma unroll
;         for (int i = 0; i < 2; ++i) { const int id = tid + i * NTHREADS, row = id >> 3, cc = id & 7;
;             const u32x4 v = *(const u32x4*)(Vg + (size_t)(c * 128 + row) * VD + cc * 8);
;             *(LAS u32x4*)(Vs + row * VS_STRIDE + cc * 16) = v;
;             const float sw = __builtin_amdgcn_exp2f((float)(127 - row) * log2g);
;             u32x4 w; w.x = cvt_pk_bf16(bflo(v.x) * sw, bfhi(v.x) * sw); w.y = cvt_pk_bf16(bflo(v.y) * sw, bfhi(v.y) * sw); w.z = cvt_pk_bf16(bflo(v.z) * sw, bfhi(v.z) * sw); w.w = cvt_pk_bf16(bflo(v.w) * sw, bfhi(v.w) * sw);
;             *(LAS u32x4*)(Vw + row * VS_STRIDE + cc * 16) = w; }
;         bf16x8 qf[8];
; #pragma unroll
;         for (int ks = 0; ks < 8; ++ks) qf[ks] = *(const bf16x8*)(Qg + (size_t)(c * 128 + 16 * wid + fr) * D + ks * 32 + fq * 8);
;         __syncthreads();
.LBB0_1046:
	s_lshl_b32 s23, s57, 17
	v_or_b32_e32 v50, s23, v191
	v_or_b32_e32 v52, s23, v192
	v_or_b32_e32 v58, s23, v193
	v_or_b32_e32 v60, s23, v194
	v_lshlrev_b32_e32 v50, 1, v50
	v_mov_b32_e32 v51, v119
	v_lshlrev_b32_e32 v52, 1, v52
	v_mov_b32_e32 v53, v119
	v_lshlrev_b32_e32 v58, 1, v58
	v_mov_b32_e32 v59, v119
	v_lshlrev_b32_e32 v60, 1, v60
	v_mov_b32_e32 v61, v119
	v_lshl_add_u64 v[50:51], v[120:121], 0, v[50:51]
	v_lshl_add_u64 v[54:55], v[120:121], 0, v[52:53]
	v_lshl_add_u64 v[58:59], v[120:121], 0, v[58:59]
	v_lshl_add_u64 v[62:63], v[120:121], 0, v[60:61]
	global_load_dwordx4 v[50:53], v[50:51], off
	s_nop 0
	global_load_dwordx4 v[54:57], v[54:55], off
	s_nop 0
	global_load_dwordx4 v[58:61], v[58:59], off
	s_nop 0
	global_load_dwordx4 v[62:65], v[62:63], off
	v_or_b32_e32 v66, s23, v195
	v_or_b32_e32 v68, s23, v196
	v_lshlrev_b32_e32 v66, 1, v66
	v_mov_b32_e32 v67, v119
	v_lshlrev_b32_e32 v68, 1, v68
	v_mov_b32_e32 v69, v119
	v_or_b32_e32 v74, s23, v197
	v_lshl_add_u64 v[66:67], v[120:121], 0, v[66:67]
	v_lshl_add_u64 v[70:71], v[120:121], 0, v[68:69]
	v_lshlrev_b32_e32 v74, 1, v74
	v_mov_b32_e32 v75, v119
	v_add_lshl_u32 v76, s23, v198, 1
	v_mov_b32_e32 v77, v119
	global_load_dwordx4 v[66:69], v[66:67], off
	s_nop 0
	global_load_dwordx4 v[70:73], v[70:71], off
	v_lshl_add_u64 v[74:75], v[120:121], 0, v[74:75]
	v_lshl_add_u64 v[78:79], v[120:121], 0, v[76:77]
	global_load_dwordx4 v[74:77], v[74:75], off
	s_nop 0
	global_load_dwordx4 v[78:81], v[78:79], off
	s_lshl_b32 s23, s57, 18
	v_or_b32_e32 v82, s23, v199
	v_lshlrev_b32_e32 v82, 1, v82
	v_mov_b32_e32 v83, v119
	v_lshl_add_u64 v[82:83], v[122:123], 0, v[82:83]
	global_load_dwordx4 v[178:181], v[82:83], off
	v_add_lshl_u32 v82, s23, v201, 1
	v_mov_b32_e32 v83, v119
	v_lshl_add_u64 v[82:83], v[122:123], 0, v[82:83]
	global_load_dwordx4 v[222:225], v[82:83], off
	s_lshl_b32 s23, s57, 7
	v_mov_b32_e32 v83, v119
	v_add_u32_e32 v82, s23, v186
	v_lshlrev_b64 v[82:83], 11, v[82:83]
	v_lshl_add_u64 v[110:111], v[124:125], 0, v[82:83]
	global_load_dwordx4 v[82:85], v[110:111], off
	global_load_dwordx4 v[86:89], v[110:111], off offset:64
	global_load_dwordx4 v[90:93], v[110:111], off offset:128
	global_load_dwordx4 v[94:97], v[110:111], off offset:192
	global_load_dwordx4 v[98:101], v[110:111], off offset:256
	v_cvt_pk_bf16_f32 v102, v30, v31
	v_cvt_pk_bf16_f32 v103, v32, v33
	v_cvt_pk_bf16_f32 v112, v2, v3
	v_cvt_pk_bf16_f32 v113, v4, v5
	v_cvt_pk_bf16_f32 v104, v18, v19
	v_cvt_pk_bf16_f32 v105, v20, v21
	v_cvt_pk_bf16_f32 v106, v22, v23
	v_cvt_pk_bf16_f32 v107, v24, v25
	v_cvt_pk_bf16_f32 v226, v6, v7
	v_cvt_pk_bf16_f32 v227, v8, v9
	v_add_u32_e32 v117, 0x2000, v208
	v_cvt_pk_bf16_f32 v228, v10, v11
	v_cvt_pk_bf16_f32 v229, v12, v13
	v_add_u32_e32 v161, 0x4000, v208
	ds_write2_b64 v208, v[102:103], v[112:113] offset1:4
	ds_write2_b64 v117, v[104:105], v[226:227] offset0:32 offset1:36
	ds_write2_b64 v161, v[106:107], v[228:229] offset0:64 offset1:68
	global_load_dwordx4 v[102:105], v[110:111], off offset:320
	v_cvt_pk_bf16_f32 v108, v26, v27
	v_cvt_pk_bf16_f32 v109, v28, v29
	v_cvt_pk_bf16_f32 v230, v14, v15
	v_cvt_pk_bf16_f32 v231, v16, v17
	v_add_u32_e32 v163, 0x6000, v208
	v_lshl_or_b32 v161, s58, 5, v183
	v_lshlrev_b32_e32 v182, 9, v161
	s_mov_b32 s26, 0
	v_mov_b32_e32 v117, v204
	s_mov_b32 s27, s37
	ds_write2_b64 v163, v[108:109], v[230:231] offset0:96 offset1:100
	s_waitcnt vmcnt(15)
	ds_write_b128 v209, v[50:53]
	s_waitcnt vmcnt(14)
	ds_write_b128 v210, v[54:57]
	s_waitcnt vmcnt(13)
	ds_write_b128 v209, v[58:61] offset:16896
	s_waitcnt vmcnt(12)
	ds_write_b128 v211, v[62:65]
	global_load_dwordx4 v[106:109], v[110:111], off offset:384
	s_waitcnt vmcnt(12)
	ds_write_b128 v209, v[66:69] offset:33792
	s_waitcnt vmcnt(11)
	ds_write_b128 v212, v[70:73]
	s_waitcnt vmcnt(10)
	ds_write_b128 v209, v[74:77] offset:50688
	global_load_dwordx4 v[110:113], v[110:111], off offset:448
	v_add_u32_e32 v50, v184, v200
	s_waitcnt vmcnt(10)
	ds_write_b128 v213, v[78:81]
	v_mov_b32_e32 v163, v139
	s_waitcnt vmcnt(9)
	ds_write_b128 v50, v[178:181]
	v_lshlrev_b32_e32 v50, 16, v178
	v_and_b32_e32 v51, 0xffff0000, v178
	v_lshlrev_b32_e32 v52, 16, v179
	v_and_b32_e32 v53, 0xffff0000, v179
	v_pk_mul_f32 v[50:51], v[140:141], v[50:51]
	v_pk_mul_f32 v[52:53], v[140:141], v[52:53]
	v_cvt_pk_bf16_f32 v50, v50, v51
	v_cvt_pk_bf16_f32 v51, v52, v53
	v_lshlrev_b32_e32 v52, 16, v180
	v_and_b32_e32 v53, 0xffff0000, v180
	v_lshlrev_b32_e32 v54, 16, v181
	v_and_b32_e32 v55, 0xffff0000, v181
	v_pk_mul_f32 v[52:53], v[140:141], v[52:53]
	v_pk_mul_f32 v[54:55], v[140:141], v[54:55]
	v_cvt_pk_bf16_f32 v52, v52, v53
	v_cvt_pk_bf16_f32 v53, v54, v55
	v_add_u32_e32 v54, v185, v200
	ds_write_b128 v54, v[50:53]
	v_add_u32_e32 v50, v184, v202
	s_waitcnt vmcnt(8)
	ds_write_b128 v50, v[222:225]
	v_lshlrev_b32_e32 v50, 16, v222
	v_and_b32_e32 v51, 0xffff0000, v222
	v_lshlrev_b32_e32 v52, 16, v223
	v_and_b32_e32 v53, 0xffff0000, v223
	v_pk_mul_f32 v[50:51], v[142:143], v[50:51]
	v_pk_mul_f32 v[52:53], v[142:143], v[52:53]
	v_cvt_pk_bf16_f32 v50, v50, v51
	v_cvt_pk_bf16_f32 v51, v52, v53
	v_lshlrev_b32_e32 v52, 16, v224
	v_and_b32_e32 v53, 0xffff0000, v224
	v_lshlrev_b32_e32 v54, 16, v225
	v_and_b32_e32 v55, 0xffff0000, v225
	v_pk_mul_f32 v[52:53], v[142:143], v[52:53]
	v_pk_mul_f32 v[54:55], v[142:143], v[54:55]
	v_cvt_pk_bf16_f32 v52, v52, v53
	v_cvt_pk_bf16_f32 v53, v54, v55
	v_add_u32_e32 v54, v185, v202
	ds_write_b128 v54, v[50:53]
	s_waitcnt lgkmcnt(0)
	s_barrier
; #define LAS __attribute__((address_space(3)))
; #define SAMPLE_ISSUE(hb) do { _Pragma("unroll") for (int i = 0; i < 4; ++i) s0v[i] = __builtin_nontemporal_load((const f32x4*)(S0 + (size_t)(dbase + 4 * ((hb) * 4 + i)) * 512)); } while (0)
; __device__ __forceinline__ void retention_fused(const Params& p, LAS unsigned char* lds, int unit) {
;     ...
;         SAMPLE_ISSUE(0);
;         f32x4 o[4];
; #pragma unroll
;         for (int nt = 0; nt < 4; ++nt) {
;             o[nt] = (f32x4){0.f, 0.f, 0.f, 0.f};
; #pragma unroll
;             for (int ks = 0; ks < 8; ++ks) { const bf16x8 sf = *(const LAS bf16x8*)(St + (nt * 16 + fr) * ST_STRIDE + ks * 64 + fq * 16);
;                 o[nt] = __builtin_amdgcn_mfma_f32_16x16x32_bf16(qf[ks], sf, o[nt], 0, 0, 0); }
; #pragma unroll
;             for (int r = 0; r < 4; ++r) o[nt][r] *= __builtin_amdgcn_exp2f((float)(16 * wid + fq * 4 + r + 1) * log2g);
;         }
	ds_read_b128 v[226:229], v214
	ds_read_b128 v[230:233], v214 offset:64
	ds_read_b128 v[234:237], v214 offset:128
	ds_read_b128 v[238:241], v214 offset:192
	ds_read_b128 v[242:245], v214 offset:256
	ds_read_b128 v[248:251], v214 offset:320
	ds_read_b128 v[252:255], v214 offset:384
	v_lshlrev_b32_e32 v178, 11, v161
	v_mov_b32_e32 v179, v119
	v_lshl_add_u64 v[180:181], v[164:165], 0, v[178:179]
	global_load_dwordx4 v[78:81], v[180:181], off nt
	v_add_co_u32_e32 v70, vcc, s52, v180
	s_nop 1
	v_addc_co_u32_e32 v71, vcc, 0, v181, vcc
	global_load_dwordx4 v[74:77], v[70:71], off nt
	v_add_co_u32_e32 v66, vcc, s51, v180
	s_nop 1
	v_addc_co_u32_e32 v67, vcc, 0, v181, vcc
	v_add_co_u32_e32 v68, vcc, s53, v180
	s_nop 1
	v_addc_co_u32_e32 v69, vcc, 0, v181, vcc
	global_load_dwordx4 v[70:73], v[66:67], off nt
	s_nop 0
	global_load_dwordx4 v[66:69], v[68:69], off nt
	s_waitcnt vmcnt(11) lgkmcnt(6)
	v_mfma_f32_16x16x32_bf16 v[62:65], v[82:85], v[226:229], 0
	ds_read_b128 v[222:225], v214 offset:448
	s_waitcnt vmcnt(10) lgkmcnt(6)
	v_mfma_f32_16x16x32_bf16 v[62:65], v[86:89], v[230:233], v[62:65]
	ds_read_b128 v[226:229], v214 offset:8448
	s_waitcnt vmcnt(9) lgkmcnt(6)
	v_mfma_f32_16x16x32_bf16 v[62:65], v[90:93], v[234:237], v[62:65]
	ds_read_b128 v[230:233], v214 offset:8512
	s_waitcnt vmcnt(8) lgkmcnt(6)
	v_mfma_f32_16x16x32_bf16 v[62:65], v[94:97], v[238:241], v[62:65]
	ds_read_b128 v[234:237], v214 offset:8576
	s_waitcnt vmcnt(7) lgkmcnt(6)
	v_mfma_f32_16x16x32_bf16 v[62:65], v[98:101], v[242:245], v[62:65]
	ds_read_b128 v[238:241], v214 offset:8640
	s_waitcnt vmcnt(6) lgkmcnt(6)
	v_mfma_f32_16x16x32_bf16 v[62:65], v[102:105], v[248:251], v[62:65]
	ds_read_b128 v[242:245], v214 offset:8704
	s_waitcnt vmcnt(5) lgkmcnt(6)
	v_mfma_f32_16x16x32_bf16 v[62:65], v[106:109], v[252:255], v[62:65]
	ds_read_b128 v[248:251], v214 offset:8768
	s_waitcnt vmcnt(4) lgkmcnt(6)
	v_mfma_f32_16x16x32_bf16 v[62:65], v[110:113], v[222:225], v[62:65]
	ds_read_b128 v[252:255], v214 offset:8832
	s_waitcnt lgkmcnt(6)
	v_mfma_f32_16x16x32_bf16 v[58:61], v[82:85], v[226:229], 0
	ds_read_b128 v[222:225], v214 offset:8896
	s_waitcnt lgkmcnt(6)
	v_mfma_f32_16x16x32_bf16 v[58:61], v[86:89], v[230:233], v[58:61]
	ds_read_b128 v[226:229], v214 offset:16896
	s_waitcnt lgkmcnt(6)
	v_mfma_f32_16x16x32_bf16 v[58:61], v[90:93], v[234:237], v[58:61]
	ds_read_b128 v[230:233], v214 offset:16960
	s_waitcnt lgkmcnt(6)
	v_mfma_f32_16x16x32_bf16 v[58:61], v[94:97], v[238:241], v[58:61]
	ds_read_b128 v[234:237], v214 offset:17024
	s_waitcnt lgkmcnt(6)
	v_mfma_f32_16x16x32_bf16 v[58:61], v[98:101], v[242:245], v[58:61]
	ds_read_b128 v[238:241], v214 offset:17088
	s_waitcnt lgkmcnt(6)
	v_mfma_f32_16x16x32_bf16 v[58:61], v[102:105], v[248:251], v[58:61]
	ds_read_b128 v[242:245], v214 offset:17152
	s_waitcnt lgkmcnt(6)
	v_mfma_f32_16x16x32_bf16 v[58:61], v[106:109], v[252:255], v[58:61]
	ds_read_b128 v[248:251], v214 offset:17216
	s_waitcnt lgkmcnt(6)
	v_mfma_f32_16x16x32_bf16 v[58:61], v[110:113], v[222:225], v[58:61]
	ds_read_b128 v[252:255], v214 offset:17280
	s_waitcnt lgkmcnt(6)
	v_mfma_f32_16x16x32_bf16 v[54:57], v[82:85], v[226:229], 0
	ds_read_b128 v[222:225], v214 offset:17344
	s_waitcnt lgkmcnt(6)
	v_mfma_f32_16x16x32_bf16 v[54:57], v[86:89], v[230:233], v[54:57]
	ds_read_b128 v[226:229], v214 offset:25344
	s_waitcnt lgkmcnt(6)
	v_mfma_f32_16x16x32_bf16 v[54:57], v[90:93], v[234:237], v[54:57]
	ds_read_b128 v[230:233], v214 offset:25408
	v_pk_mul_f32 v[62:63], v[144:145], v[62:63]
	s_waitcnt lgkmcnt(6)
	v_mfma_f32_16x16x32_bf16 v[54:57], v[94:97], v[238:241], v[54:57]
	ds_read_b128 v[234:237], v214 offset:25472
	s_waitcnt lgkmcnt(6)
	v_mfma_f32_16x16x32_bf16 v[54:57], v[98:101], v[242:245], v[54:57]
	ds_read_b128 v[238:241], v214 offset:25536
	v_pk_mul_f32 v[64:65], v[148:149], v[64:65]
	s_waitcnt lgkmcnt(6)
	v_mfma_f32_16x16x32_bf16 v[54:57], v[102:105], v[248:251], v[54:57]
	ds_read_b128 v[242:245], v214 offset:25600
	s_waitcnt lgkmcnt(6)
	v_mfma_f32_16x16x32_bf16 v[54:57], v[106:109], v[252:255], v[54:57]
	ds_read_b128 v[248:251], v214 offset:25664
	s_waitcnt lgkmcnt(6)
	v_mfma_f32_16x16x32_bf16 v[54:57], v[110:113], v[222:225], v[54:57]
	ds_read_b128 v[252:255], v214 offset:25728
	s_waitcnt lgkmcnt(6)
	v_mfma_f32_16x16x32_bf16 v[50:53], v[82:85], v[226:229], 0
	ds_read_b128 v[222:225], v214 offset:25792
	s_waitcnt lgkmcnt(6)
	v_mfma_f32_16x16x32_bf16 v[50:53], v[86:89], v[230:233], v[50:53]
	s_waitcnt lgkmcnt(5)
	v_mfma_f32_16x16x32_bf16 v[50:53], v[90:93], v[234:237], v[50:53]
	v_pk_mul_f32 v[58:59], v[144:145], v[58:59]
	s_waitcnt lgkmcnt(4)
	v_mfma_f32_16x16x32_bf16 v[50:53], v[94:97], v[238:241], v[50:53]
	s_waitcnt lgkmcnt(3)
	v_mfma_f32_16x16x32_bf16 v[50:53], v[98:101], v[242:245], v[50:53]
	v_pk_mul_f32 v[60:61], v[148:149], v[60:61]
	s_waitcnt lgkmcnt(2)
	v_mfma_f32_16x16x32_bf16 v[50:53], v[102:105], v[248:251], v[50:53]
	s_waitcnt lgkmcnt(1)
	v_mfma_f32_16x16x32_bf16 v[50:53], v[106:109], v[252:255], v[50:53]
	s_waitcnt lgkmcnt(0)
	v_mfma_f32_16x16x32_bf16 v[50:53], v[110:113], v[222:225], v[50:53]
	ds_read_b128 v[248:251], v163
	ds_read_b128 v[252:255], v163 offset:64
	v_pk_mul_f32 v[54:55], v[144:145], v[54:55]
	v_pk_mul_f32 v[56:57], v[148:149], v[56:57]
	s_nop 3
	v_pk_mul_f32 v[50:51], v[144:145], v[50:51]
	v_pk_mul_f32 v[52:53], v[148:149], v[52:53]
	s_branch .LBB0_1049
